# DA loop: scalar-op diet in PV gaps combined with the two-op row-max tail
# speedup vs baseline: 1.0029x; 1.0002x over previous
; #define SCHED_FENCE() __builtin_amdgcn_sched_barrier(0)
; __device__ __forceinline__ void da_phase(LAS unsigned char* lds, const bf16* Q, const bf16* Kb, const bf16* Vb, bf16* O, const float* lq1, const float* lk1, const float* lq2, const float* lk2,
;                                          const float* t5, int G, int wave, int lane, int tid) {
;     ...
;             p1 = __builtin_amdgcn_mfma_f32_32x32x16_bf16(__builtin_bit_cast(H8, kf[0]), qf[0], p1, 0, 0, 0); a0 = __builtin_fmaxf(__builtin_fmaxf(p0[0], p0[1]), p0[2]); a0 = __builtin_fmaxf(__builtin_fmaxf(a0, p0[3]), p0[4]); asm volatile("" : "+v"(a0)); SCHED_FENCE();
;             p1 = __builtin_amdgcn_mfma_f32_32x32x16_bf16(__builtin_bit_cast(H8, kf[1]), qf[1], p1, 0, 0, 0); a0 = __builtin_fmaxf(__builtin_fmaxf(a0, p0[5]), p0[6]); a0 = __builtin_fmaxf(__builtin_fmaxf(a0, p0[7]), p0[8]); asm volatile("" : "+v"(a0)); SCHED_FENCE();
;             p1 = __builtin_amdgcn_mfma_f32_32x32x16_bf16(__builtin_bit_cast(H8, kf[2]), qf[2], p1, 0, 0, 0); a0 = __builtin_fmaxf(__builtin_fmaxf(a0, p0[9]), p0[10]); a0 = __builtin_fmaxf(__builtin_fmaxf(a0, p0[11]), p0[12]); asm volatile("" : "+v"(a0)); SCHED_FENCE();
;             p1 = __builtin_amdgcn_mfma_f32_32x32x16_bf16(__builtin_bit_cast(H8, kf[3]), qf[3], p1, 0, 0, 0); a0 = __builtin_fmaxf(__builtin_fmaxf(a0, p0[13]), p0[14]); a0 = __builtin_fmaxf(a0, p0[15]); asm volatile("" : "+v"(a0)); SCHED_FENCE();
;             if (t + 2 < NT) DA_DMA_V(t + 2, (t + 2) & 3);
.LBB0_217:
	s_waitcnt lgkmcnt(0)
	v_mfma_f32_32x32x16_bf16 v[80:95], v[176:179], v[120:123], v[236:251]
	ds_read_b64_tr_b16 v[160:161], v234 offset:0
	ds_read_b64_tr_b16 v[162:163], v234 offset:512
	ds_read_b64_tr_b16 v[156:157], v234 offset:1024
	ds_read_b64_tr_b16 v[158:159], v234 offset:1536
	v_max3_f32 v0, v96, v97, v98
	v_max3_f32 v0, v0, v99, v100
	v_mfma_f32_32x32x16_bf16 v[80:95], v[172:175], v[124:127], v[80:95]
	ds_read_b64_tr_b16 v[152:153], v234 offset:2048
	ds_read_b64_tr_b16 v[154:155], v234 offset:2560
	ds_read_b64_tr_b16 v[148:149], v234 offset:3072
	ds_read_b64_tr_b16 v[150:151], v234 offset:3584
	v_max3_f32 v0, v0, v101, v102
	v_max3_f32 v0, v0, v103, v104
	v_mfma_f32_32x32x16_bf16 v[80:95], v[168:171], v[128:131], v[80:95]
	ds_read_b64_tr_b16 v[144:145], v234 offset:4096
	ds_read_b64_tr_b16 v[146:147], v234 offset:4608
	ds_read_b64_tr_b16 v[10:11], v234 offset:5120
	ds_read_b64_tr_b16 v[12:13], v234 offset:5632
	v_max3_f32 v0, v0, v105, v106
	v_max3_f32 v0, v0, v107, v108
	v_mfma_f32_32x32x16_bf16 v[80:95], v[164:167], v[132:135], v[80:95]
	ds_read_b64_tr_b16 v[6:7], v234 offset:6144
	ds_read_b64_tr_b16 v[8:9], v234 offset:6656
	ds_read_b64_tr_b16 v[2:3], v234 offset:7168
	ds_read_b64_tr_b16 v[4:5], v234 offset:7680
	v_max3_f32 v0, v0, v109, v110
	v_max_f32_e32 v0, v0, v111
	s_cmp_gt_i32 s44, s20
	s_cbranch_scc1 .Lda_vskip
	s_add_i32 s0, s16, 0x4000
	s_and_b32 s0, s0, 0xc000
	s_add_i32 s0, s3, s0
	s_add_i32 m0, s0, 0xc000
	s_nop 0
	global_load_lds_dwordx4 v196, s[74:75]
	s_add_i32 m0, m0, 0x400
	s_nop 0
	global_load_lds_dwordx4 v205, s[74:75]
	s_add_u32 s74, s74, 0x4000
	s_addc_u32 s75, s75, 0
